# static_setprio1_waves4to7_in_nsa_loop
# speedup vs baseline: 1.0020x; 1.0020x over previous
.LBB0_421:
	s_add_i32 s0, 0, 0x22ff0
	v_writelane_b32 v254, s0, 7
	s_waitcnt vmcnt(2)
	v_mov_b32_e32 v91, s0
	s_add_i32 s0, 0, 0x19c00
	v_writelane_b32 v254, s0, 8
	s_add_i32 s0, 0, 0x1bc00
	v_writelane_b32 v254, s0, 9
	v_writelane_b32 v254, s86, 10
	v_cmp_eq_u32_e64 s[8:9], 0, v113
	s_add_i32 s65, 0, 0x11c00
	v_writelane_b32 v254, s87, 11
	v_writelane_b32 v254, s88, 12
	s_mov_b32 s43, 0
	v_mov_b32_e32 v77, 0
	v_writelane_b32 v254, s89, 13
	v_writelane_b32 v254, s90, 14
	s_movk_i32 s10, 0x90
	s_waitcnt vmcnt(1)
	v_mov_b32_e32 v92, 0xf149f2ca
	v_writelane_b32 v254, s91, 15
	v_writelane_b32 v254, s92, 16
	v_mbcnt_hi_u32_b32 v174, -1, v230
	v_mov_b32_e32 v93, 0x80
	v_writelane_b32 v254, s93, 17
	v_writelane_b32 v254, s85, 18
	v_writelane_b32 v254, s94, 19
	v_mov_b32_e32 v94, 0x100
	v_mov_b32_e32 v95, 0x200
	v_writelane_b32 v254, s95, 20
	v_writelane_b32 v254, s71, 21
	v_writelane_b32 v254, s72, 22
	v_writelane_b32 v254, s74, 23
	s_waitcnt vmcnt(0)
	v_mov_b32_e32 v96, 0x400
	v_mov_b32_e32 v97, 0x800
	v_writelane_b32 v254, s75, 24
	v_writelane_b32 v254, s96, 25
	v_writelane_b32 v254, s97, 26
	v_writelane_b32 v254, s66, 27
	v_mov_b32_e32 v98, 0x1000
	v_mov_b32_e32 v99, 0x2000
	v_writelane_b32 v254, s67, 28
	v_writelane_b32 v254, s8, 29
	v_mov_b32_e32 v100, 0x4000
	v_mov_b32_e32 v101, 0x8000
	v_writelane_b32 v254, s9, 30
	v_mov_b32_e32 v102, 0xff800000
	v_writelane_b32 v254, s65, 31
	s_mov_b32 s99, 0
	v_readfirstlane_b32 s100, v210
	s_lshr_b32 s100, s100, 8
	s_cmp_eq_u32 s100, 0
	s_cbranch_scc1 .Lnsa_prio_done
	s_setprio 1
.Lnsa_prio_done:
	s_branch .LBB0_424

.LBB0_613:
	s_setprio 0
	s_getreg_b32 s2, hwreg(HW_REG_XCC_ID, 0, 4)
	s_waitcnt vmcnt(0)
	s_barrier
	s_mov_b64 s[0:1], exec
	v_readlane_b32 s4, v253, 10
	v_readlane_b32 s5, v253, 11
	s_and_b64 s[4:5], s[0:1], s[4:5]
	s_mov_b64 exec, s[4:5]
	s_cbranch_execz .LBB0_636
	s_add_i32 s3, 0, 0x22fe0
	v_mov_b32_e32 v0, s3
	s_add_i32 s3, 0, 0x22fe4
	s_waitcnt vmcnt(0) expcnt(0) lgkmcnt(0)
	ds_read_b32 v1, v0
	v_mov_b32_e32 v0, s3
	ds_read_b32 v0, v0
	s_mov_b64 s[4:5], exec
	s_lshl_b32 s2, s2, 8
	s_and_b32 s2, s2, 0xf00
	v_readlane_b32 s6, v253, 8
	v_mbcnt_lo_u32_b32 v2, s4, 0
	v_readlane_b32 s7, v253, 9
	s_add_u32 s2, s6, s2
	v_mbcnt_hi_u32_b32 v2, s5, v2
	s_addc_u32 s3, s7, 0
	v_cmp_eq_u32_e32 vcc, 0, v2
	s_and_saveexec_b64 s[6:7], vcc
	s_cbranch_execz .LBB0_616
	s_bcnt1_i32_b64 s4, s[4:5]
	v_mov_b32_e32 v3, 0x1000
	v_mov_b32_e32 v4, s4
	global_atomic_add v3, v3, v4, s[2:3] offset:1024 sc0
